# v5 + adaLN GEMV k-loop software-pipelined (prefetch next 4 weight rows under the FMAs, counted vmcnt)
# baseline (speedup 1.0000x reference)
; __device__ __forceinline__ void phase_prologue(const Args& A, LAS unsigned char* lds, int tid, int wid, int lane) {
;     ...
;     for (int item = blockIdx.x; item < DEPTH * 48; item += gridDim.x) {
;         const int layer = item / 48, cb = item % 48, col = cb * 128 + (lane & 31) * 4, ks = wid * 2 + (lane >> 5);
;         const float* wp = A.in[I_ADAW] + ((size_t)layer * DM + ks * 128) * (3 * DM) + col;
;         f32x4 acc[NB];
; #pragma unroll
;         for (int b = 0; b < NB; ++b) acc[b] = (f32x4){0.f, 0.f, 0.f, 0.f};
; #pragma unroll 4
;         for (int kk = 0; kk < 128; ++kk) { const f32x4 w = *(const f32x4*)(wp + (size_t)kk * (3 * DM));
; #pragma unroll
;             for (int b = 0; b < NB; ++b) { const float cv = condL[b * DM + ks * 128 + kk]; acc[b] += w * cv; } }
.LBB0_564:
	s_mul_hi_i32 s0, s8, 0x2aaaaaab
	s_lshr_b32 s1, s0, 31
	s_ashr_i32 s0, s0, 3
	s_add_i32 s2, s0, s1
	v_lshl_or_b32 v0, s8, 7, v52
	s_mul_i32 s6, s2, 0x1800
	v_subrev_u32_e32 v2, s6, v0
	v_ashrrev_i32_e32 v3, 31, v2
	v_lshlrev_b64 v[2:3], 2, v[2:3]
	v_mad_i64_i32 v[2:3], s[0:1], s2, v210, v[2:3]
	v_lshl_add_u64 v[60:61], v[58:59], 0, v[2:3]
	v_mov_b32_e32 v2, 0
	s_ashr_i32 s3, s2, 31
	s_mov_b64 s[4:5], 0
	v_mov_b32_e32 v0, v51
	v_mov_b32_e32 v3, v2
	v_mov_b32_e32 v4, v2
	v_mov_b32_e32 v5, v2
	v_mov_b32_e32 v6, v2
	v_mov_b32_e32 v7, v2
	v_mov_b32_e32 v8, v2
	v_mov_b32_e32 v9, v2
	v_mov_b32_e32 v10, v2
	v_mov_b32_e32 v11, v2
	v_mov_b32_e32 v12, v2
	v_mov_b32_e32 v13, v2
	v_mov_b32_e32 v14, v2
	v_mov_b32_e32 v15, v2
	v_mov_b32_e32 v16, v2
	v_mov_b32_e32 v17, v2
	v_mov_b32_e32 v18, v2
	v_mov_b32_e32 v19, v2
	v_mov_b32_e32 v20, v2
	v_mov_b32_e32 v21, v2
	v_mov_b32_e32 v22, v2
	v_mov_b32_e32 v23, v2
	v_mov_b32_e32 v24, v2
	v_mov_b32_e32 v25, v2
	v_mov_b32_e32 v26, v2
	v_mov_b32_e32 v27, v2
	v_mov_b32_e32 v28, v2
	v_mov_b32_e32 v29, v2
	v_mov_b32_e32 v30, v2
	v_mov_b32_e32 v31, v2
	v_mov_b32_e32 v32, v2
	v_mov_b32_e32 v33, v2
	v_lshl_add_u64 v[68:69], v[60:61], 0, s[4:5]
	v_add_co_u32_e64 v70, s[0:1], s83, v68
	s_nop 0
	s_nop 0
	s_nop 0
	s_nop 0
	v_addc_co_u32_e64 v71, s[0:1], 0, v69, s[0:1]
	v_add_co_u32_e64 v72, s[0:1], s33, v68
	global_load_dwordx4 v[64:67], v[68:69], off
	s_nop 0
	v_addc_co_u32_e64 v73, s[0:1], 0, v69, s[0:1]
	s_mov_b32 s0, 0x12000
	s_nop 0
	v_add_co_u32_e64 v76, s[0:1], s0, v68
	s_add_u32 s4, s4, 0x18000
	s_nop 0
	v_addc_co_u32_e64 v77, s[0:1], 0, v69, s[0:1]
	global_load_dwordx4 v[68:71], v[70:71], off
	s_nop 0
	global_load_dwordx4 v[72:75], v[72:73], off
	s_nop 0
	global_load_dwordx4 v[76:79], v[76:77], off
	s_addc_u32 s5, s5, 0
.LBB0_565:
	s_cmp_eq_u32 s4, 0x300000
	s_cbranch_scc1 .Lada_tailA
	v_lshl_add_u64 v[116:117], v[60:61], 0, s[4:5]
	v_add_co_u32_e64 v118, s[0:1], s83, v116
	s_nop 0
	s_nop 0
	s_nop 0
	s_nop 0
	v_addc_co_u32_e64 v119, s[0:1], 0, v117, s[0:1]
	v_add_co_u32_e64 v120, s[0:1], s33, v116
	global_load_dwordx4 v[112:115], v[116:117], off
	s_nop 0
	v_addc_co_u32_e64 v121, s[0:1], 0, v117, s[0:1]
	s_mov_b32 s0, 0x12000
	s_nop 0
	v_add_co_u32_e64 v124, s[0:1], s0, v116
	s_add_u32 s4, s4, 0x18000
	s_nop 0
	v_addc_co_u32_e64 v125, s[0:1], 0, v117, s[0:1]
	global_load_dwordx4 v[116:119], v[118:119], off
	s_nop 0
	global_load_dwordx4 v[120:123], v[120:121], off
	s_nop 0
	global_load_dwordx4 v[124:127], v[124:125], off
	s_addc_u32 s5, s5, 0
	ds_read_b128 v[34:37], v0
	ds_read_b128 v[38:41], v0 offset:8192
	ds_read_b128 v[42:45], v0 offset:16384
	ds_read_b128 v[46:49], v0 offset:24576
	ds_read_b128 v[80:83], v0 offset:32768
	ds_read_b128 v[84:87], v0 offset:40960
	ds_read_b128 v[88:91], v0 offset:49152
	ds_read_b128 v[92:95], v0 offset:57344
	s_waitcnt lgkmcnt(0)
	v_mov_b32_e32 v96, v37
	v_mov_b32_e32 v98, v41
	v_mov_b32_e32 v100, v45
	v_mov_b32_e32 v102, v49
	v_mov_b32_e32 v104, v83
	v_mov_b32_e32 v106, v87
	v_mov_b32_e32 v108, v91
	v_mov_b32_e32 v110, v95
	v_add_u32_e32 v0, 16, v0
	s_waitcnt vmcnt(4)
	v_pk_fma_f32 v[8:9], v[66:67], v[34:35], v[8:9] op_sel_hi:[1,0,1]
	v_pk_fma_f32 v[6:7], v[64:65], v[34:35], v[6:7] op_sel_hi:[1,0,1]
	v_pk_fma_f32 v[12:13], v[66:67], v[38:39], v[12:13] op_sel_hi:[1,0,1]
	v_pk_fma_f32 v[10:11], v[64:65], v[38:39], v[10:11] op_sel_hi:[1,0,1]
	v_pk_fma_f32 v[16:17], v[66:67], v[42:43], v[16:17] op_sel_hi:[1,0,1]
	v_pk_fma_f32 v[14:15], v[64:65], v[42:43], v[14:15] op_sel_hi:[1,0,1]
	v_pk_fma_f32 v[20:21], v[66:67], v[46:47], v[20:21] op_sel_hi:[1,0,1]
	v_pk_fma_f32 v[18:19], v[64:65], v[46:47], v[18:19] op_sel_hi:[1,0,1]
	v_pk_fma_f32 v[24:25], v[66:67], v[80:81], v[24:25] op_sel_hi:[1,0,1]
	v_pk_fma_f32 v[22:23], v[64:65], v[80:81], v[22:23] op_sel_hi:[1,0,1]
	v_pk_fma_f32 v[28:29], v[66:67], v[84:85], v[28:29] op_sel_hi:[1,0,1]
	v_pk_fma_f32 v[26:27], v[64:65], v[84:85], v[26:27] op_sel_hi:[1,0,1]
	v_pk_fma_f32 v[32:33], v[66:67], v[88:89], v[32:33] op_sel_hi:[1,0,1]
	v_pk_fma_f32 v[30:31], v[64:65], v[88:89], v[30:31] op_sel_hi:[1,0,1]
	v_pk_fma_f32 v[4:5], v[66:67], v[92:93], v[4:5] op_sel_hi:[1,0,1]
	v_pk_fma_f32 v[2:3], v[64:65], v[92:93], v[2:3] op_sel_hi:[1,0,1]
	v_pk_fma_f32 v[6:7], v[68:69], v[34:35], v[6:7] op_sel:[0,1,0]
	v_pk_fma_f32 v[8:9], v[70:71], v[34:35], v[8:9] op_sel:[0,1,0]
	v_pk_fma_f32 v[10:11], v[68:69], v[38:39], v[10:11] op_sel:[0,1,0]
	v_pk_fma_f32 v[12:13], v[70:71], v[38:39], v[12:13] op_sel:[0,1,0]
	v_pk_fma_f32 v[14:15], v[68:69], v[42:43], v[14:15] op_sel:[0,1,0]
	v_pk_fma_f32 v[16:17], v[70:71], v[42:43], v[16:17] op_sel:[0,1,0]
	v_pk_fma_f32 v[18:19], v[68:69], v[46:47], v[18:19] op_sel:[0,1,0]
	v_pk_fma_f32 v[20:21], v[70:71], v[46:47], v[20:21] op_sel:[0,1,0]
	v_pk_fma_f32 v[22:23], v[68:69], v[80:81], v[22:23] op_sel:[0,1,0]
	v_pk_fma_f32 v[24:25], v[70:71], v[80:81], v[24:25] op_sel:[0,1,0]
	v_pk_fma_f32 v[26:27], v[68:69], v[84:85], v[26:27] op_sel:[0,1,0]
	v_pk_fma_f32 v[28:29], v[70:71], v[84:85], v[28:29] op_sel:[0,1,0]
	v_pk_fma_f32 v[30:31], v[68:69], v[88:89], v[30:31] op_sel:[0,1,0]
	v_pk_fma_f32 v[32:33], v[70:71], v[88:89], v[32:33] op_sel:[0,1,0]
	v_pk_fma_f32 v[2:3], v[68:69], v[92:93], v[2:3] op_sel:[0,1,0]
	v_pk_fma_f32 v[4:5], v[70:71], v[92:93], v[4:5] op_sel:[0,1,0]
	v_pk_fma_f32 v[8:9], v[74:75], v[36:37], v[8:9] op_sel_hi:[1,0,1]
	v_pk_fma_f32 v[6:7], v[72:73], v[36:37], v[6:7] op_sel_hi:[1,0,1]
	v_pk_fma_f32 v[12:13], v[74:75], v[40:41], v[12:13] op_sel_hi:[1,0,1]
	v_pk_fma_f32 v[10:11], v[72:73], v[40:41], v[10:11] op_sel_hi:[1,0,1]
	v_pk_fma_f32 v[16:17], v[74:75], v[44:45], v[16:17] op_sel_hi:[1,0,1]
; __device__ __forceinline__ void phase_prologue(const Args& A, LAS unsigned char* lds, int tid, int wid, int lane) {
;     ...
; #pragma unroll 4
;         for (int kk = 0; kk < 128; ++kk) { const f32x4 w = *(const f32x4*)(wp + (size_t)kk * (3 * DM));
; #pragma unroll
;             for (int b = 0; b < NB; ++b) { const float cv = condL[b * DM + ks * 128 + kk]; acc[b] += w * cv; } }
	v_pk_fma_f32 v[14:15], v[72:73], v[44:45], v[14:15] op_sel_hi:[1,0,1]
	v_pk_fma_f32 v[20:21], v[74:75], v[48:49], v[20:21] op_sel_hi:[1,0,1]
	v_pk_fma_f32 v[18:19], v[72:73], v[48:49], v[18:19] op_sel_hi:[1,0,1]
	v_pk_fma_f32 v[24:25], v[74:75], v[82:83], v[24:25] op_sel_hi:[1,0,1]
	v_pk_fma_f32 v[22:23], v[72:73], v[82:83], v[22:23] op_sel_hi:[1,0,1]
	v_pk_fma_f32 v[28:29], v[74:75], v[86:87], v[28:29] op_sel_hi:[1,0,1]
	v_pk_fma_f32 v[26:27], v[72:73], v[86:87], v[26:27] op_sel_hi:[1,0,1]
	v_pk_fma_f32 v[32:33], v[74:75], v[90:91], v[32:33] op_sel_hi:[1,0,1]
	v_pk_fma_f32 v[30:31], v[72:73], v[90:91], v[30:31] op_sel_hi:[1,0,1]
	v_pk_fma_f32 v[4:5], v[74:75], v[94:95], v[4:5] op_sel_hi:[1,0,1]
	v_pk_fma_f32 v[2:3], v[72:73], v[94:95], v[2:3] op_sel_hi:[1,0,1]
	v_pk_fma_f32 v[8:9], v[78:79], v[96:97], v[8:9] op_sel_hi:[1,0,1]
	v_pk_fma_f32 v[6:7], v[76:77], v[96:97], v[6:7] op_sel_hi:[1,0,1]
	v_pk_fma_f32 v[12:13], v[78:79], v[98:99], v[12:13] op_sel_hi:[1,0,1]
	v_pk_fma_f32 v[10:11], v[76:77], v[98:99], v[10:11] op_sel_hi:[1,0,1]
	v_pk_fma_f32 v[16:17], v[78:79], v[100:101], v[16:17] op_sel_hi:[1,0,1]
	v_pk_fma_f32 v[14:15], v[76:77], v[100:101], v[14:15] op_sel_hi:[1,0,1]
	v_pk_fma_f32 v[20:21], v[78:79], v[102:103], v[20:21] op_sel_hi:[1,0,1]
	v_pk_fma_f32 v[18:19], v[76:77], v[102:103], v[18:19] op_sel_hi:[1,0,1]
	v_pk_fma_f32 v[24:25], v[78:79], v[104:105], v[24:25] op_sel_hi:[1,0,1]
	v_pk_fma_f32 v[22:23], v[76:77], v[104:105], v[22:23] op_sel_hi:[1,0,1]
	v_pk_fma_f32 v[28:29], v[78:79], v[106:107], v[28:29] op_sel_hi:[1,0,1]
	v_pk_fma_f32 v[26:27], v[76:77], v[106:107], v[26:27] op_sel_hi:[1,0,1]
	v_pk_fma_f32 v[32:33], v[78:79], v[108:109], v[32:33] op_sel_hi:[1,0,1]
	v_pk_fma_f32 v[30:31], v[76:77], v[108:109], v[30:31] op_sel_hi:[1,0,1]
	v_pk_fma_f32 v[4:5], v[78:79], v[110:111], v[4:5] op_sel_hi:[1,0,1]
	v_pk_fma_f32 v[2:3], v[76:77], v[110:111], v[2:3] op_sel_hi:[1,0,1]
	s_cmp_eq_u32 s4, 0x300000
	s_cbranch_scc1 .Lada_tailB
	v_lshl_add_u64 v[68:69], v[60:61], 0, s[4:5]
	v_add_co_u32_e64 v70, s[0:1], s83, v68
	s_nop 0
	s_nop 0
	s_nop 0
	s_nop 0
	v_addc_co_u32_e64 v71, s[0:1], 0, v69, s[0:1]
	v_add_co_u32_e64 v72, s[0:1], s33, v68
	global_load_dwordx4 v[64:67], v[68:69], off
	s_nop 0
	v_addc_co_u32_e64 v73, s[0:1], 0, v69, s[0:1]
	s_mov_b32 s0, 0x12000
	s_nop 0
	v_add_co_u32_e64 v76, s[0:1], s0, v68
	s_add_u32 s4, s4, 0x18000
	s_nop 0
	v_addc_co_u32_e64 v77, s[0:1], 0, v69, s[0:1]
	global_load_dwordx4 v[68:71], v[70:71], off
	s_nop 0
	global_load_dwordx4 v[72:75], v[72:73], off
	s_nop 0
	global_load_dwordx4 v[76:79], v[76:77], off
	s_addc_u32 s5, s5, 0
	ds_read_b128 v[34:37], v0
	ds_read_b128 v[38:41], v0 offset:8192
	ds_read_b128 v[42:45], v0 offset:16384
	ds_read_b128 v[46:49], v0 offset:24576
	ds_read_b128 v[80:83], v0 offset:32768
	ds_read_b128 v[84:87], v0 offset:40960
	ds_read_b128 v[88:91], v0 offset:49152
	ds_read_b128 v[92:95], v0 offset:57344
	s_waitcnt lgkmcnt(0)
	v_mov_b32_e32 v96, v37
	v_mov_b32_e32 v98, v41
	v_mov_b32_e32 v100, v45
	v_mov_b32_e32 v102, v49
	v_mov_b32_e32 v104, v83
	v_mov_b32_e32 v106, v87
	v_mov_b32_e32 v108, v91
	v_mov_b32_e32 v110, v95
	v_add_u32_e32 v0, 16, v0
	s_waitcnt vmcnt(4)
	v_pk_fma_f32 v[8:9], v[114:115], v[34:35], v[8:9] op_sel_hi:[1,0,1]
	v_pk_fma_f32 v[6:7], v[112:113], v[34:35], v[6:7] op_sel_hi:[1,0,1]
	v_pk_fma_f32 v[12:13], v[114:115], v[38:39], v[12:13] op_sel_hi:[1,0,1]
	v_pk_fma_f32 v[10:11], v[112:113], v[38:39], v[10:11] op_sel_hi:[1,0,1]
	v_pk_fma_f32 v[16:17], v[114:115], v[42:43], v[16:17] op_sel_hi:[1,0,1]
	v_pk_fma_f32 v[14:15], v[112:113], v[42:43], v[14:15] op_sel_hi:[1,0,1]
	v_pk_fma_f32 v[20:21], v[114:115], v[46:47], v[20:21] op_sel_hi:[1,0,1]
	v_pk_fma_f32 v[18:19], v[112:113], v[46:47], v[18:19] op_sel_hi:[1,0,1]
	v_pk_fma_f32 v[24:25], v[114:115], v[80:81], v[24:25] op_sel_hi:[1,0,1]
	v_pk_fma_f32 v[22:23], v[112:113], v[80:81], v[22:23] op_sel_hi:[1,0,1]
	v_pk_fma_f32 v[28:29], v[114:115], v[84:85], v[28:29] op_sel_hi:[1,0,1]
	v_pk_fma_f32 v[26:27], v[112:113], v[84:85], v[26:27] op_sel_hi:[1,0,1]
	v_pk_fma_f32 v[32:33], v[114:115], v[88:89], v[32:33] op_sel_hi:[1,0,1]
	v_pk_fma_f32 v[30:31], v[112:113], v[88:89], v[30:31] op_sel_hi:[1,0,1]
	v_pk_fma_f32 v[4:5], v[114:115], v[92:93], v[4:5] op_sel_hi:[1,0,1]
	v_pk_fma_f32 v[2:3], v[112:113], v[92:93], v[2:3] op_sel_hi:[1,0,1]
	v_pk_fma_f32 v[6:7], v[116:117], v[34:35], v[6:7] op_sel:[0,1,0]
	v_pk_fma_f32 v[8:9], v[118:119], v[34:35], v[8:9] op_sel:[0,1,0]
	v_pk_fma_f32 v[10:11], v[116:117], v[38:39], v[10:11] op_sel:[0,1,0]
	v_pk_fma_f32 v[12:13], v[118:119], v[38:39], v[12:13] op_sel:[0,1,0]
	v_pk_fma_f32 v[14:15], v[116:117], v[42:43], v[14:15] op_sel:[0,1,0]
	v_pk_fma_f32 v[16:17], v[118:119], v[42:43], v[16:17] op_sel:[0,1,0]
	v_pk_fma_f32 v[18:19], v[116:117], v[46:47], v[18:19] op_sel:[0,1,0]
	v_pk_fma_f32 v[20:21], v[118:119], v[46:47], v[20:21] op_sel:[0,1,0]
	v_pk_fma_f32 v[22:23], v[116:117], v[80:81], v[22:23] op_sel:[0,1,0]
	v_pk_fma_f32 v[24:25], v[118:119], v[80:81], v[24:25] op_sel:[0,1,0]
	v_pk_fma_f32 v[26:27], v[116:117], v[84:85], v[26:27] op_sel:[0,1,0]
	v_pk_fma_f32 v[28:29], v[118:119], v[84:85], v[28:29] op_sel:[0,1,0]
	v_pk_fma_f32 v[30:31], v[116:117], v[88:89], v[30:31] op_sel:[0,1,0]
	v_pk_fma_f32 v[32:33], v[118:119], v[88:89], v[32:33] op_sel:[0,1,0]
	v_pk_fma_f32 v[2:3], v[116:117], v[92:93], v[2:3] op_sel:[0,1,0]
	v_pk_fma_f32 v[4:5], v[118:119], v[92:93], v[4:5] op_sel:[0,1,0]
	v_pk_fma_f32 v[8:9], v[122:123], v[36:37], v[8:9] op_sel_hi:[1,0,1]
	v_pk_fma_f32 v[6:7], v[120:121], v[36:37], v[6:7] op_sel_hi:[1,0,1]
	v_pk_fma_f32 v[12:13], v[122:123], v[40:41], v[12:13] op_sel_hi:[1,0,1]
; __device__ __forceinline__ void phase_prologue(const Args& A, LAS unsigned char* lds, int tid, int wid, int lane) {
;     ...
; #pragma unroll 4
;         for (int kk = 0; kk < 128; ++kk) { const f32x4 w = *(const f32x4*)(wp + (size_t)kk * (3 * DM));
; #pragma unroll
;             for (int b = 0; b < NB; ++b) { const float cv = condL[b * DM + ks * 128 + kk]; acc[b] += w * cv; } }
	v_pk_fma_f32 v[10:11], v[120:121], v[40:41], v[10:11] op_sel_hi:[1,0,1]
	v_pk_fma_f32 v[16:17], v[122:123], v[44:45], v[16:17] op_sel_hi:[1,0,1]
	v_pk_fma_f32 v[14:15], v[120:121], v[44:45], v[14:15] op_sel_hi:[1,0,1]
	v_pk_fma_f32 v[20:21], v[122:123], v[48:49], v[20:21] op_sel_hi:[1,0,1]
	v_pk_fma_f32 v[18:19], v[120:121], v[48:49], v[18:19] op_sel_hi:[1,0,1]
	v_pk_fma_f32 v[24:25], v[122:123], v[82:83], v[24:25] op_sel_hi:[1,0,1]
	v_pk_fma_f32 v[22:23], v[120:121], v[82:83], v[22:23] op_sel_hi:[1,0,1]
	v_pk_fma_f32 v[28:29], v[122:123], v[86:87], v[28:29] op_sel_hi:[1,0,1]
	v_pk_fma_f32 v[26:27], v[120:121], v[86:87], v[26:27] op_sel_hi:[1,0,1]
	v_pk_fma_f32 v[32:33], v[122:123], v[90:91], v[32:33] op_sel_hi:[1,0,1]
	v_pk_fma_f32 v[30:31], v[120:121], v[90:91], v[30:31] op_sel_hi:[1,0,1]
	v_pk_fma_f32 v[4:5], v[122:123], v[94:95], v[4:5] op_sel_hi:[1,0,1]
	v_pk_fma_f32 v[2:3], v[120:121], v[94:95], v[2:3] op_sel_hi:[1,0,1]
	v_pk_fma_f32 v[8:9], v[126:127], v[96:97], v[8:9] op_sel_hi:[1,0,1]
	v_pk_fma_f32 v[6:7], v[124:125], v[96:97], v[6:7] op_sel_hi:[1,0,1]
	v_pk_fma_f32 v[12:13], v[126:127], v[98:99], v[12:13] op_sel_hi:[1,0,1]
	v_pk_fma_f32 v[10:11], v[124:125], v[98:99], v[10:11] op_sel_hi:[1,0,1]
	v_pk_fma_f32 v[16:17], v[126:127], v[100:101], v[16:17] op_sel_hi:[1,0,1]
	v_pk_fma_f32 v[14:15], v[124:125], v[100:101], v[14:15] op_sel_hi:[1,0,1]
	v_pk_fma_f32 v[20:21], v[126:127], v[102:103], v[20:21] op_sel_hi:[1,0,1]
	v_pk_fma_f32 v[18:19], v[124:125], v[102:103], v[18:19] op_sel_hi:[1,0,1]
	v_pk_fma_f32 v[24:25], v[126:127], v[104:105], v[24:25] op_sel_hi:[1,0,1]
	v_pk_fma_f32 v[22:23], v[124:125], v[104:105], v[22:23] op_sel_hi:[1,0,1]
	v_pk_fma_f32 v[28:29], v[126:127], v[106:107], v[28:29] op_sel_hi:[1,0,1]
	v_pk_fma_f32 v[26:27], v[124:125], v[106:107], v[26:27] op_sel_hi:[1,0,1]
	v_pk_fma_f32 v[32:33], v[126:127], v[108:109], v[32:33] op_sel_hi:[1,0,1]
	v_pk_fma_f32 v[30:31], v[124:125], v[108:109], v[30:31] op_sel_hi:[1,0,1]
	v_pk_fma_f32 v[4:5], v[126:127], v[110:111], v[4:5] op_sel_hi:[1,0,1]
	v_pk_fma_f32 v[2:3], v[124:125], v[110:111], v[2:3] op_sel_hi:[1,0,1]
	s_branch .LBB0_565
.Lada_tailA:
	ds_read_b128 v[34:37], v0
	ds_read_b128 v[38:41], v0 offset:8192
	ds_read_b128 v[42:45], v0 offset:16384
	ds_read_b128 v[46:49], v0 offset:24576
	ds_read_b128 v[80:83], v0 offset:32768
	ds_read_b128 v[84:87], v0 offset:40960
	ds_read_b128 v[88:91], v0 offset:49152
	ds_read_b128 v[92:95], v0 offset:57344
	s_waitcnt lgkmcnt(0)
	v_mov_b32_e32 v96, v37
	v_mov_b32_e32 v98, v41
	v_mov_b32_e32 v100, v45
	v_mov_b32_e32 v102, v49
	v_mov_b32_e32 v104, v83
	v_mov_b32_e32 v106, v87
	v_mov_b32_e32 v108, v91
	v_mov_b32_e32 v110, v95
	v_add_u32_e32 v0, 16, v0
	s_waitcnt vmcnt(0)
	v_pk_fma_f32 v[8:9], v[66:67], v[34:35], v[8:9] op_sel_hi:[1,0,1]
	v_pk_fma_f32 v[6:7], v[64:65], v[34:35], v[6:7] op_sel_hi:[1,0,1]
	v_pk_fma_f32 v[12:13], v[66:67], v[38:39], v[12:13] op_sel_hi:[1,0,1]
	v_pk_fma_f32 v[10:11], v[64:65], v[38:39], v[10:11] op_sel_hi:[1,0,1]
	v_pk_fma_f32 v[16:17], v[66:67], v[42:43], v[16:17] op_sel_hi:[1,0,1]
	v_pk_fma_f32 v[14:15], v[64:65], v[42:43], v[14:15] op_sel_hi:[1,0,1]
	v_pk_fma_f32 v[20:21], v[66:67], v[46:47], v[20:21] op_sel_hi:[1,0,1]
	v_pk_fma_f32 v[18:19], v[64:65], v[46:47], v[18:19] op_sel_hi:[1,0,1]
	v_pk_fma_f32 v[24:25], v[66:67], v[80:81], v[24:25] op_sel_hi:[1,0,1]
	v_pk_fma_f32 v[22:23], v[64:65], v[80:81], v[22:23] op_sel_hi:[1,0,1]
	v_pk_fma_f32 v[28:29], v[66:67], v[84:85], v[28:29] op_sel_hi:[1,0,1]
	v_pk_fma_f32 v[26:27], v[64:65], v[84:85], v[26:27] op_sel_hi:[1,0,1]
	v_pk_fma_f32 v[32:33], v[66:67], v[88:89], v[32:33] op_sel_hi:[1,0,1]
	v_pk_fma_f32 v[30:31], v[64:65], v[88:89], v[30:31] op_sel_hi:[1,0,1]
	v_pk_fma_f32 v[4:5], v[66:67], v[92:93], v[4:5] op_sel_hi:[1,0,1]
	v_pk_fma_f32 v[2:3], v[64:65], v[92:93], v[2:3] op_sel_hi:[1,0,1]
	v_pk_fma_f32 v[6:7], v[68:69], v[34:35], v[6:7] op_sel:[0,1,0]
	v_pk_fma_f32 v[8:9], v[70:71], v[34:35], v[8:9] op_sel:[0,1,0]
	v_pk_fma_f32 v[10:11], v[68:69], v[38:39], v[10:11] op_sel:[0,1,0]
	v_pk_fma_f32 v[12:13], v[70:71], v[38:39], v[12:13] op_sel:[0,1,0]
	v_pk_fma_f32 v[14:15], v[68:69], v[42:43], v[14:15] op_sel:[0,1,0]
	v_pk_fma_f32 v[16:17], v[70:71], v[42:43], v[16:17] op_sel:[0,1,0]
	v_pk_fma_f32 v[18:19], v[68:69], v[46:47], v[18:19] op_sel:[0,1,0]
	v_pk_fma_f32 v[20:21], v[70:71], v[46:47], v[20:21] op_sel:[0,1,0]
	v_pk_fma_f32 v[22:23], v[68:69], v[80:81], v[22:23] op_sel:[0,1,0]
	v_pk_fma_f32 v[24:25], v[70:71], v[80:81], v[24:25] op_sel:[0,1,0]
	v_pk_fma_f32 v[26:27], v[68:69], v[84:85], v[26:27] op_sel:[0,1,0]
	v_pk_fma_f32 v[28:29], v[70:71], v[84:85], v[28:29] op_sel:[0,1,0]
	v_pk_fma_f32 v[30:31], v[68:69], v[88:89], v[30:31] op_sel:[0,1,0]
	v_pk_fma_f32 v[32:33], v[70:71], v[88:89], v[32:33] op_sel:[0,1,0]
	v_pk_fma_f32 v[2:3], v[68:69], v[92:93], v[2:3] op_sel:[0,1,0]
	v_pk_fma_f32 v[4:5], v[70:71], v[92:93], v[4:5] op_sel:[0,1,0]
	v_pk_fma_f32 v[8:9], v[74:75], v[36:37], v[8:9] op_sel_hi:[1,0,1]
	v_pk_fma_f32 v[6:7], v[72:73], v[36:37], v[6:7] op_sel_hi:[1,0,1]
	v_pk_fma_f32 v[12:13], v[74:75], v[40:41], v[12:13] op_sel_hi:[1,0,1]
	v_pk_fma_f32 v[10:11], v[72:73], v[40:41], v[10:11] op_sel_hi:[1,0,1]
	v_pk_fma_f32 v[16:17], v[74:75], v[44:45], v[16:17] op_sel_hi:[1,0,1]
	v_pk_fma_f32 v[14:15], v[72:73], v[44:45], v[14:15] op_sel_hi:[1,0,1]
	v_pk_fma_f32 v[20:21], v[74:75], v[48:49], v[20:21] op_sel_hi:[1,0,1]
	v_pk_fma_f32 v[18:19], v[72:73], v[48:49], v[18:19] op_sel_hi:[1,0,1]
	v_pk_fma_f32 v[24:25], v[74:75], v[82:83], v[24:25] op_sel_hi:[1,0,1]
	v_pk_fma_f32 v[22:23], v[72:73], v[82:83], v[22:23] op_sel_hi:[1,0,1]
; __device__ __forceinline__ void phase_prologue(const Args& A, LAS unsigned char* lds, int tid, int wid, int lane) {
;     ...
; #pragma unroll 4
;         for (int kk = 0; kk < 128; ++kk) { const f32x4 w = *(const f32x4*)(wp + (size_t)kk * (3 * DM));
; #pragma unroll
;             for (int b = 0; b < NB; ++b) { const float cv = condL[b * DM + ks * 128 + kk]; acc[b] += w * cv; } }
	v_pk_fma_f32 v[28:29], v[74:75], v[86:87], v[28:29] op_sel_hi:[1,0,1]
	v_pk_fma_f32 v[26:27], v[72:73], v[86:87], v[26:27] op_sel_hi:[1,0,1]
	v_pk_fma_f32 v[32:33], v[74:75], v[90:91], v[32:33] op_sel_hi:[1,0,1]
	v_pk_fma_f32 v[30:31], v[72:73], v[90:91], v[30:31] op_sel_hi:[1,0,1]
	v_pk_fma_f32 v[4:5], v[74:75], v[94:95], v[4:5] op_sel_hi:[1,0,1]
	v_pk_fma_f32 v[2:3], v[72:73], v[94:95], v[2:3] op_sel_hi:[1,0,1]
	v_pk_fma_f32 v[8:9], v[78:79], v[96:97], v[8:9] op_sel_hi:[1,0,1]
	v_pk_fma_f32 v[6:7], v[76:77], v[96:97], v[6:7] op_sel_hi:[1,0,1]
	v_pk_fma_f32 v[12:13], v[78:79], v[98:99], v[12:13] op_sel_hi:[1,0,1]
	v_pk_fma_f32 v[10:11], v[76:77], v[98:99], v[10:11] op_sel_hi:[1,0,1]
	v_pk_fma_f32 v[16:17], v[78:79], v[100:101], v[16:17] op_sel_hi:[1,0,1]
	v_pk_fma_f32 v[14:15], v[76:77], v[100:101], v[14:15] op_sel_hi:[1,0,1]
	v_pk_fma_f32 v[20:21], v[78:79], v[102:103], v[20:21] op_sel_hi:[1,0,1]
	v_pk_fma_f32 v[18:19], v[76:77], v[102:103], v[18:19] op_sel_hi:[1,0,1]
	v_pk_fma_f32 v[24:25], v[78:79], v[104:105], v[24:25] op_sel_hi:[1,0,1]
	v_pk_fma_f32 v[22:23], v[76:77], v[104:105], v[22:23] op_sel_hi:[1,0,1]
	v_pk_fma_f32 v[28:29], v[78:79], v[106:107], v[28:29] op_sel_hi:[1,0,1]
	v_pk_fma_f32 v[26:27], v[76:77], v[106:107], v[26:27] op_sel_hi:[1,0,1]
	v_pk_fma_f32 v[32:33], v[78:79], v[108:109], v[32:33] op_sel_hi:[1,0,1]
	v_pk_fma_f32 v[30:31], v[76:77], v[108:109], v[30:31] op_sel_hi:[1,0,1]
	v_pk_fma_f32 v[4:5], v[78:79], v[110:111], v[4:5] op_sel_hi:[1,0,1]
	v_pk_fma_f32 v[2:3], v[76:77], v[110:111], v[2:3] op_sel_hi:[1,0,1]
	s_branch .Lada_done
; #define LAS __attribute__((address_space(3)))
; __device__ __forceinline__ void phase_prologue(const Args& A, LAS unsigned char* lds, int tid, int wid, int lane) {
;     ...
; #pragma unroll 4
;         for (int kk = 0; kk < 128; ++kk) { const f32x4 w = *(const f32x4*)(wp + (size_t)kk * (3 * DM));
; #pragma unroll
;             for (int b = 0; b < NB; ++b) { const float cv = condL[b * DM + ks * 128 + kk]; acc[b] += w * cv; } }
; #pragma unroll
;         for (int b = 0; b < NB; ++b) *(LAS f32x4*)(red + (ks * NB + b) * 128 + (lane & 31) * 4) = acc[b];
;         __syncthreads();
;         for (int o = tid; o < NB * 128; o += NTHREADS) { const int b = o >> 7, c = o & 127; float s = A.in[I_ADAB][layer * 3 * DM + cb * 128 + c];
.Lada_tailB:
	ds_read_b128 v[34:37], v0
	ds_read_b128 v[38:41], v0 offset:8192
	ds_read_b128 v[42:45], v0 offset:16384
	ds_read_b128 v[46:49], v0 offset:24576
	ds_read_b128 v[80:83], v0 offset:32768
	ds_read_b128 v[84:87], v0 offset:40960
	ds_read_b128 v[88:91], v0 offset:49152
	ds_read_b128 v[92:95], v0 offset:57344
	s_waitcnt lgkmcnt(0)
	v_mov_b32_e32 v96, v37
	v_mov_b32_e32 v98, v41
	v_mov_b32_e32 v100, v45
	v_mov_b32_e32 v102, v49
	v_mov_b32_e32 v104, v83
	v_mov_b32_e32 v106, v87
	v_mov_b32_e32 v108, v91
	v_mov_b32_e32 v110, v95
	v_add_u32_e32 v0, 16, v0
	s_waitcnt vmcnt(0)
	v_pk_fma_f32 v[8:9], v[114:115], v[34:35], v[8:9] op_sel_hi:[1,0,1]
	v_pk_fma_f32 v[6:7], v[112:113], v[34:35], v[6:7] op_sel_hi:[1,0,1]
	v_pk_fma_f32 v[12:13], v[114:115], v[38:39], v[12:13] op_sel_hi:[1,0,1]
	v_pk_fma_f32 v[10:11], v[112:113], v[38:39], v[10:11] op_sel_hi:[1,0,1]
	v_pk_fma_f32 v[16:17], v[114:115], v[42:43], v[16:17] op_sel_hi:[1,0,1]
	v_pk_fma_f32 v[14:15], v[112:113], v[42:43], v[14:15] op_sel_hi:[1,0,1]
	v_pk_fma_f32 v[20:21], v[114:115], v[46:47], v[20:21] op_sel_hi:[1,0,1]
	v_pk_fma_f32 v[18:19], v[112:113], v[46:47], v[18:19] op_sel_hi:[1,0,1]
	v_pk_fma_f32 v[24:25], v[114:115], v[80:81], v[24:25] op_sel_hi:[1,0,1]
	v_pk_fma_f32 v[22:23], v[112:113], v[80:81], v[22:23] op_sel_hi:[1,0,1]
	v_pk_fma_f32 v[28:29], v[114:115], v[84:85], v[28:29] op_sel_hi:[1,0,1]
	v_pk_fma_f32 v[26:27], v[112:113], v[84:85], v[26:27] op_sel_hi:[1,0,1]
	v_pk_fma_f32 v[32:33], v[114:115], v[88:89], v[32:33] op_sel_hi:[1,0,1]
	v_pk_fma_f32 v[30:31], v[112:113], v[88:89], v[30:31] op_sel_hi:[1,0,1]
	v_pk_fma_f32 v[4:5], v[114:115], v[92:93], v[4:5] op_sel_hi:[1,0,1]
	v_pk_fma_f32 v[2:3], v[112:113], v[92:93], v[2:3] op_sel_hi:[1,0,1]
	v_pk_fma_f32 v[6:7], v[116:117], v[34:35], v[6:7] op_sel:[0,1,0]
	v_pk_fma_f32 v[8:9], v[118:119], v[34:35], v[8:9] op_sel:[0,1,0]
	v_pk_fma_f32 v[10:11], v[116:117], v[38:39], v[10:11] op_sel:[0,1,0]
	v_pk_fma_f32 v[12:13], v[118:119], v[38:39], v[12:13] op_sel:[0,1,0]
	v_pk_fma_f32 v[14:15], v[116:117], v[42:43], v[14:15] op_sel:[0,1,0]
	v_pk_fma_f32 v[16:17], v[118:119], v[42:43], v[16:17] op_sel:[0,1,0]
	v_pk_fma_f32 v[18:19], v[116:117], v[46:47], v[18:19] op_sel:[0,1,0]
	v_pk_fma_f32 v[20:21], v[118:119], v[46:47], v[20:21] op_sel:[0,1,0]
	v_pk_fma_f32 v[22:23], v[116:117], v[80:81], v[22:23] op_sel:[0,1,0]
	v_pk_fma_f32 v[24:25], v[118:119], v[80:81], v[24:25] op_sel:[0,1,0]
	v_pk_fma_f32 v[26:27], v[116:117], v[84:85], v[26:27] op_sel:[0,1,0]
	v_pk_fma_f32 v[28:29], v[118:119], v[84:85], v[28:29] op_sel:[0,1,0]
	v_pk_fma_f32 v[30:31], v[116:117], v[88:89], v[30:31] op_sel:[0,1,0]
	v_pk_fma_f32 v[32:33], v[118:119], v[88:89], v[32:33] op_sel:[0,1,0]
	v_pk_fma_f32 v[2:3], v[116:117], v[92:93], v[2:3] op_sel:[0,1,0]
	v_pk_fma_f32 v[4:5], v[118:119], v[92:93], v[4:5] op_sel:[0,1,0]
	v_pk_fma_f32 v[8:9], v[122:123], v[36:37], v[8:9] op_sel_hi:[1,0,1]
	v_pk_fma_f32 v[6:7], v[120:121], v[36:37], v[6:7] op_sel_hi:[1,0,1]
	v_pk_fma_f32 v[12:13], v[122:123], v[40:41], v[12:13] op_sel_hi:[1,0,1]
	v_pk_fma_f32 v[10:11], v[120:121], v[40:41], v[10:11] op_sel_hi:[1,0,1]
	v_pk_fma_f32 v[16:17], v[122:123], v[44:45], v[16:17] op_sel_hi:[1,0,1]
	v_pk_fma_f32 v[14:15], v[120:121], v[44:45], v[14:15] op_sel_hi:[1,0,1]
	v_pk_fma_f32 v[20:21], v[122:123], v[48:49], v[20:21] op_sel_hi:[1,0,1]
	v_pk_fma_f32 v[18:19], v[120:121], v[48:49], v[18:19] op_sel_hi:[1,0,1]
	v_pk_fma_f32 v[24:25], v[122:123], v[82:83], v[24:25] op_sel_hi:[1,0,1]
	v_pk_fma_f32 v[22:23], v[120:121], v[82:83], v[22:23] op_sel_hi:[1,0,1]
	v_pk_fma_f32 v[28:29], v[122:123], v[86:87], v[28:29] op_sel_hi:[1,0,1]
	v_pk_fma_f32 v[26:27], v[120:121], v[86:87], v[26:27] op_sel_hi:[1,0,1]
	v_pk_fma_f32 v[32:33], v[122:123], v[90:91], v[32:33] op_sel_hi:[1,0,1]
	v_pk_fma_f32 v[30:31], v[120:121], v[90:91], v[30:31] op_sel_hi:[1,0,1]
	v_pk_fma_f32 v[4:5], v[122:123], v[94:95], v[4:5] op_sel_hi:[1,0,1]
	v_pk_fma_f32 v[2:3], v[120:121], v[94:95], v[2:3] op_sel_hi:[1,0,1]
	v_pk_fma_f32 v[8:9], v[126:127], v[96:97], v[8:9] op_sel_hi:[1,0,1]
	v_pk_fma_f32 v[6:7], v[124:125], v[96:97], v[6:7] op_sel_hi:[1,0,1]
	v_pk_fma_f32 v[12:13], v[126:127], v[98:99], v[12:13] op_sel_hi:[1,0,1]
	v_pk_fma_f32 v[10:11], v[124:125], v[98:99], v[10:11] op_sel_hi:[1,0,1]
	v_pk_fma_f32 v[16:17], v[126:127], v[100:101], v[16:17] op_sel_hi:[1,0,1]
	v_pk_fma_f32 v[14:15], v[124:125], v[100:101], v[14:15] op_sel_hi:[1,0,1]
	v_pk_fma_f32 v[20:21], v[126:127], v[102:103], v[20:21] op_sel_hi:[1,0,1]
	v_pk_fma_f32 v[18:19], v[124:125], v[102:103], v[18:19] op_sel_hi:[1,0,1]
	v_pk_fma_f32 v[24:25], v[126:127], v[104:105], v[24:25] op_sel_hi:[1,0,1]
	v_pk_fma_f32 v[22:23], v[124:125], v[104:105], v[22:23] op_sel_hi:[1,0,1]
	v_pk_fma_f32 v[28:29], v[126:127], v[106:107], v[28:29] op_sel_hi:[1,0,1]
	v_pk_fma_f32 v[26:27], v[124:125], v[106:107], v[26:27] op_sel_hi:[1,0,1]
	v_pk_fma_f32 v[32:33], v[126:127], v[108:109], v[32:33] op_sel_hi:[1,0,1]
	v_pk_fma_f32 v[30:31], v[124:125], v[108:109], v[30:31] op_sel_hi:[1,0,1]
	v_pk_fma_f32 v[4:5], v[126:127], v[110:111], v[4:5] op_sel_hi:[1,0,1]
	v_pk_fma_f32 v[2:3], v[124:125], v[110:111], v[2:3] op_sel_hi:[1,0,1]
.Lada_done:
	ds_write_b128 v53, v[6:9]
	ds_write_b128 v53, v[10:13] offset:512
	ds_write_b128 v53, v[14:17] offset:1024
	ds_write_b128 v53, v[18:21] offset:1536
	ds_write_b128 v53, v[22:25] offset:2048
	ds_write_b128 v53, v[26:29] offset:2560
	ds_write_b128 v53, v[30:33] offset:3072
	ds_write_b128 v53, v[2:5] offset:3584
	s_waitcnt lgkmcnt(0)
	s_barrier
	s_and_saveexec_b64 s[4:5], vcc
	s_cbranch_execz .LBB0_563
	s_mul_i32 s0, s2, 48
	s_sub_i32 s0, s8, s0
	s_lshl_b32 s0, s0, 7
	s_add_i32 s6, s6, s0
	v_or_b32_e32 v2, s6, v55
	v_readlane_b32 s16, v249, 19
	s_ashr_i32 s1, s0, 31
	v_ashrrev_i32_e32 v3, 31, v2
	v_readlane_b32 s22, v249, 25
	v_readlane_b32 s23, v249, 26
	s_lshl_b64 s[2:3], s[2:3], 3
	v_lshl_add_u64 v[4:5], s[0:1], 2, v[56:57]
	v_lshl_add_u64 v[2:3], v[2:3], 2, s[22:23]
	s_mov_b64 s[6:7], 0
	v_mov_b32_e32 v0, v196
	v_readlane_b32 s17, v249, 20
	v_readlane_b32 s18, v249, 21
	v_readlane_b32 s19, v249, 22
	v_readlane_b32 s20, v249, 23
	v_readlane_b32 s21, v249, 24
	v_readlane_b32 s24, v249, 27
	v_readlane_b32 s25, v249, 28
	v_readlane_b32 s26, v249, 29
	v_readlane_b32 s27, v249, 30
	v_readlane_b32 s28, v249, 31
	v_readlane_b32 s29, v249, 32
	v_readlane_b32 s30, v249, 33
	v_readlane_b32 s31, v249, 34
